# HGRN gate stage: 16 sigmoid/log chains issued in parallel (plus diff-attn LDS hoist)
# baseline (speedup 1.0000x reference)
; #define LAS __attribute__((address_space(3)))
; __device__ __forceinline__ unsigned short f2bf(float f) { return (unsigned short)(pk2(f, 0.f) & 0xffffu); }
; __device__ __forceinline__ float bf2f(unsigned short h) { return __uint_as_float(((unsigned)h) << 16); }
; __device__ __forceinline__ float fexp2(float x) { return __builtin_amdgcn_exp2f(x); }
; __device__ __forceinline__ float flog2(float x) { return __builtin_amdgcn_logf(x); }
; __device__ __forceinline__ float frcp(float x) { return __builtin_amdgcn_rcpf(x); }
; __device__ __forceinline__ void hgrn_unit(LAS unsigned char* lds, bf16_t* zC, int bl, int h, int dir, float lb, int tid, bf16_t* ob, int ostr, int ocol) {
;     ...
;         for (int j = 0; j < 2; ++j) { const int id = tid + j * 512; *(LAS u32x4*)(lds + HG_QE + (id >> 4) * 272 + (id & 15) * 16) = qp_[j]; *(LAS u32x4*)(lds + HG_KN + (id >> 4) * 272 + (id & 15) * 16) = fp_[j];
;             *(LAS u32x4*)(lds + HG_VV + (id >> 4) * 288 + (id & 15) * 16) = vp_[j]; }
;         __syncthreads();
;         float bl_[16], kk_[16]; float run = 0.f;
; #pragma unroll
;         for (int i = 0; i < 16; ++i) {
;             const float f = bf2f(*(const LAS unsigned short*)(lds + HG_KN + (tq * 16 + i) * 272 + k * 2));
;             const float sg = frcp(1.f + fexp2(-LOG2E * f));
;             const float fg = lb + oml * sg;
;             const float g2 = fmaxf(flog2(fg), -100.f);
;             run += g2; bl_[i] = run; kk_[i] = oml * (1.f - sg);
;         }
;         ((LAS float*)(lds + HG_SUB))[tq * 128 + k] = run;
; #pragma unroll
;         for (int kt = 0; kt < 8; ++kt)
; #pragma unroll
;             for (int j = 0; j < 4; ++j) *(LAS unsigned short*)(lds + HG_STB + (wv * 16 + quad * 4 + j) * 272 + (kt * 16 + fr) * 2) = f2bf(st[kt][j]);
.LBB0_194:
	s_waitcnt vmcnt(5)
	ds_write_b128 v105, v[8:11]
	s_waitcnt vmcnt(3)
	ds_write_b128 v105, v[16:19] offset:17408
	ds_write_b128 v106, v[12:15] offset:53248
	s_waitcnt vmcnt(2)
	ds_write_b128 v107, v[20:23]
	s_waitcnt vmcnt(1)
	ds_write_b128 v107, v[24:27] offset:17408
	s_waitcnt vmcnt(0)
	ds_write_b128 v108, v[28:31] offset:53248
	s_waitcnt lgkmcnt(0)
	s_barrier
	ds_read_u16 v192, v109 offset:17408
	ds_read_u16 v193, v109 offset:17680
	ds_read_u16 v194, v109 offset:17952
	ds_read_u16 v195, v109 offset:18224
	ds_read_u16 v196, v109 offset:18496
	ds_read_u16 v197, v109 offset:18768
	ds_read_u16 v198, v109 offset:19040
	ds_read_u16 v199, v109 offset:19312
	ds_read_u16 v200, v109 offset:19584
	ds_read_u16 v201, v109 offset:19856
	ds_read_u16 v202, v109 offset:20128
	ds_read_u16 v203, v109 offset:20400
	ds_read_u16 v204, v109 offset:20672
	ds_read_u16 v205, v109 offset:20944
	ds_read_u16 v206, v109 offset:21216
	ds_read_u16 v207, v109 offset:21488
	v_cvt_pk_bf16_f32 v208, v4, s0
	v_cvt_pk_bf16_f32 v209, v5, s0
	v_cvt_pk_bf16_f32 v210, v6, s0
	v_cvt_pk_bf16_f32 v211, v7, s0
	v_cvt_pk_bf16_f32 v212, v56, s0
	v_cvt_pk_bf16_f32 v213, v57, s0
	v_cvt_pk_bf16_f32 v214, v58, s0
	v_cvt_pk_bf16_f32 v215, v59, s0
	ds_write_b16 v110, v208
	ds_write_b16 v110, v209 offset:272
	ds_write_b16 v110, v210 offset:544
	ds_write_b16 v110, v211 offset:816
	ds_write_b16 v110, v212 offset:32
	ds_write_b16 v110, v213 offset:304
	ds_write_b16 v110, v214 offset:576
	ds_write_b16 v110, v215 offset:848
	s_waitcnt lgkmcnt(8)
	v_lshlrev_b32_e32 v192, 16, v192
	v_lshlrev_b32_e32 v193, 16, v193
	v_lshlrev_b32_e32 v194, 16, v194
	v_lshlrev_b32_e32 v195, 16, v195
	v_lshlrev_b32_e32 v196, 16, v196
	v_cvt_pk_bf16_f32 v208, v48, s0
	v_lshlrev_b32_e32 v197, 16, v197
	v_lshlrev_b32_e32 v198, 16, v198
	ds_write_b16 v110, v208 offset:64
	v_lshlrev_b32_e32 v199, 16, v199
	v_lshlrev_b32_e32 v200, 16, v200
	v_lshlrev_b32_e32 v201, 16, v201
	v_cvt_pk_bf16_f32 v209, v49, s0
	v_lshlrev_b32_e32 v202, 16, v202
	v_lshlrev_b32_e32 v203, 16, v203
	ds_write_b16 v110, v209 offset:336
	v_lshlrev_b32_e32 v204, 16, v204
	v_lshlrev_b32_e32 v205, 16, v205
	v_lshlrev_b32_e32 v206, 16, v206
	v_cvt_pk_bf16_f32 v210, v50, s0
	v_lshlrev_b32_e32 v207, 16, v207
	v_mul_f32_e32 v192, 0xbfb8aa3b, v192
	ds_write_b16 v110, v210 offset:608
	v_mul_f32_e32 v193, 0xbfb8aa3b, v193
	v_mul_f32_e32 v194, 0xbfb8aa3b, v194
	v_mul_f32_e32 v195, 0xbfb8aa3b, v195
	v_cvt_pk_bf16_f32 v211, v51, s0
	v_mul_f32_e32 v196, 0xbfb8aa3b, v196
	v_mul_f32_e32 v197, 0xbfb8aa3b, v197
	ds_write_b16 v110, v211 offset:880
	v_mul_f32_e32 v198, 0xbfb8aa3b, v198
	v_mul_f32_e32 v199, 0xbfb8aa3b, v199
	v_mul_f32_e32 v200, 0xbfb8aa3b, v200
	v_cvt_pk_bf16_f32 v212, v52, s0
	v_mul_f32_e32 v201, 0xbfb8aa3b, v201
	v_mul_f32_e32 v202, 0xbfb8aa3b, v202
	ds_write_b16 v110, v212 offset:96
	v_mul_f32_e32 v203, 0xbfb8aa3b, v203
	v_mul_f32_e32 v204, 0xbfb8aa3b, v204
	v_mul_f32_e32 v205, 0xbfb8aa3b, v205
	v_cvt_pk_bf16_f32 v213, v53, s0
	v_mul_f32_e32 v206, 0xbfb8aa3b, v206
	v_mul_f32_e32 v207, 0xbfb8aa3b, v207
	ds_write_b16 v110, v213 offset:368
	v_exp_f32_e32 v192, v192
	v_exp_f32_e32 v193, v193
	v_exp_f32_e32 v194, v194
	v_cvt_pk_bf16_f32 v214, v54, s0
	v_exp_f32_e32 v195, v195
	v_exp_f32_e32 v196, v196
	ds_write_b16 v110, v214 offset:640
	v_exp_f32_e32 v197, v197
	v_exp_f32_e32 v198, v198
	v_exp_f32_e32 v199, v199
	v_cvt_pk_bf16_f32 v215, v55, s0
	v_exp_f32_e32 v200, v200
	v_exp_f32_e32 v201, v201
	ds_write_b16 v110, v215 offset:912
	v_exp_f32_e32 v202, v202
	v_exp_f32_e32 v203, v203
	v_exp_f32_e32 v204, v204
	v_cvt_pk_bf16_f32 v208, v40, s0
	v_exp_f32_e32 v205, v205
	v_exp_f32_e32 v206, v206
	ds_write_b16 v110, v208 offset:128
	v_exp_f32_e32 v207, v207
	v_add_f32_e32 v192, 1.0, v192
	v_add_f32_e32 v193, 1.0, v193
	v_cvt_pk_bf16_f32 v209, v41, s0
	v_add_f32_e32 v194, 1.0, v194
	v_add_f32_e32 v195, 1.0, v195
	ds_write_b16 v110, v209 offset:400
	v_add_f32_e32 v196, 1.0, v196
	v_add_f32_e32 v197, 1.0, v197
	v_add_f32_e32 v198, 1.0, v198
	v_cvt_pk_bf16_f32 v210, v42, s0
	v_add_f32_e32 v199, 1.0, v199
	v_add_f32_e32 v200, 1.0, v200
	ds_write_b16 v110, v210 offset:672
	v_add_f32_e32 v201, 1.0, v201
	v_add_f32_e32 v202, 1.0, v202
	v_add_f32_e32 v203, 1.0, v203
	v_cvt_pk_bf16_f32 v211, v43, s0
	v_add_f32_e32 v204, 1.0, v204
	v_add_f32_e32 v205, 1.0, v205
	ds_write_b16 v110, v211 offset:944
	v_add_f32_e32 v206, 1.0, v206
	v_add_f32_e32 v207, 1.0, v207
	v_rcp_f32_e32 v68, v192
	v_cvt_pk_bf16_f32 v212, v44, s0
	v_rcp_f32_e32 v69, v193
	v_rcp_f32_e32 v72, v194
	ds_write_b16 v110, v212 offset:160
	v_rcp_f32_e32 v73, v195
	v_rcp_f32_e32 v74, v196
	v_rcp_f32_e32 v75, v197
	v_cvt_pk_bf16_f32 v213, v45, s0
	v_rcp_f32_e32 v60, v198
	v_rcp_f32_e32 v61, v199
	ds_write_b16 v110, v213 offset:432
	v_rcp_f32_e32 v70, v200
	v_rcp_f32_e32 v71, v201
	v_rcp_f32_e32 v66, v202
	v_cvt_pk_bf16_f32 v214, v46, s0
	v_rcp_f32_e32 v67, v203
	v_rcp_f32_e32 v64, v204
	ds_write_b16 v110, v214 offset:704
	v_rcp_f32_e32 v65, v205
	v_rcp_f32_e32 v0, v206
	v_rcp_f32_e32 v1, v207
	v_cvt_pk_bf16_f32 v215, v47, s0
	v_fma_f32 v192, v86, v68, v90
	v_fma_f32 v193, v86, v69, v90
	ds_write_b16 v110, v215 offset:976
	v_fma_f32 v194, v86, v72, v90
	v_fma_f32 v195, v86, v73, v90
	v_fma_f32 v196, v86, v74, v90
	v_cvt_pk_bf16_f32 v208, v36, s0
	v_fma_f32 v197, v86, v75, v90
	v_fma_f32 v198, v86, v60, v90
	ds_write_b16 v110, v208 offset:192
	v_fma_f32 v199, v86, v61, v90
	v_fma_f32 v200, v86, v70, v90
	v_fma_f32 v201, v86, v71, v90
	v_cvt_pk_bf16_f32 v209, v37, s0
	v_fma_f32 v202, v86, v66, v90
	v_fma_f32 v203, v86, v67, v90
	ds_write_b16 v110, v209 offset:464
	v_fma_f32 v204, v86, v64, v90
; #define LAS __attribute__((address_space(3)))
; __device__ __forceinline__ unsigned short f2bf(float f) { return (unsigned short)(pk2(f, 0.f) & 0xffffu); }
; __device__ __forceinline__ float bf2f(unsigned short h) { return __uint_as_float(((unsigned)h) << 16); }
; __device__ __forceinline__ float fexp2(float x) { return __builtin_amdgcn_exp2f(x); }
; __device__ __forceinline__ float flog2(float x) { return __builtin_amdgcn_logf(x); }
; __device__ __forceinline__ void hgrn_unit(LAS unsigned char* lds, bf16_t* zC, int bl, int h, int dir, float lb, int tid, bf16_t* ob, int ostr, int ocol) {
;     ...
;         float bl_[16], kk_[16]; float run = 0.f;
; #pragma unroll
;         for (int i = 0; i < 16; ++i) {
;             const float f = bf2f(*(const LAS unsigned short*)(lds + HG_KN + (tq * 16 + i) * 272 + k * 2));
;             const float sg = frcp(1.f + fexp2(-LOG2E * f));
;             const float fg = lb + oml * sg;
;             const float g2 = fmaxf(flog2(fg), -100.f);
;             run += g2; bl_[i] = run; kk_[i] = oml * (1.f - sg);
;         }
;         ((LAS float*)(lds + HG_SUB))[tq * 128 + k] = run;
; #pragma unroll
;         for (int kt = 0; kt < 8; ++kt)
; #pragma unroll
;             for (int j = 0; j < 4; ++j) *(LAS unsigned short*)(lds + HG_STB + (wv * 16 + quad * 4 + j) * 272 + (kt * 16 + fr) * 2) = f2bf(st[kt][j]);
;         __syncthreads();
;         {
;             const LAS float* SUB = (const LAS float*)(lds + HG_SUB);
;             const float s0 = SUB[k], s1 = SUB[128 + k], s2 = SUB[256 + k], s3 = SUB[384 + k];
;             const float bn = (tq > 0 ? s0 : 0.f) + (tq > 1 ? s1 : 0.f) + (tq > 2 ? s2 : 0.f);
;             const float btot = (s0 + s1) + (s2 + s3);
;             float ke_[16];
; #pragma unroll
;             for (int i = 0; i < 16; ++i) {
;                 const float bc = bn + bl_[i];
;                 const float q = bf2f(*(const LAS unsigned short*)(lds + HG_QE + (tq * 16 + i) * 272 + k * 2));
;                 const float qe = q * fexp2(bc);
;                 const float kn = kk_[i] * fexp2(fminf(-bc, 110.f));
;                 ke_[i] = kk_[i] * fexp2(btot - bc);
;                 *(LAS unsigned short*)(lds + HG_QE + (tq * 16 + i) * 272 + k * 2) = f2bf(qe);
;                 *(LAS unsigned short*)(lds + HG_KN + (tq * 16 + i) * 272 + k * 2) = f2bf(kn);
;             }
	v_fma_f32 v205, v86, v65, v90
	v_fma_f32 v206, v86, v0, v90
	v_cvt_pk_bf16_f32 v210, v38, s0
	v_fma_f32 v207, v86, v1, v90
	v_log_f32_e32 v192, v192
	ds_write_b16 v110, v210 offset:736
	v_log_f32_e32 v193, v193
	v_log_f32_e32 v194, v194
	v_log_f32_e32 v195, v195
	v_cvt_pk_bf16_f32 v211, v39, s0
	v_log_f32_e32 v196, v196
	v_log_f32_e32 v197, v197
	ds_write_b16 v110, v211 offset:1008
	v_log_f32_e32 v198, v198
	v_log_f32_e32 v199, v199
	v_log_f32_e32 v200, v200
	v_cvt_pk_bf16_f32 v212, v32, s0
	v_log_f32_e32 v201, v201
	v_log_f32_e32 v202, v202
	ds_write_b16 v110, v212 offset:224
	v_log_f32_e32 v203, v203
	v_log_f32_e32 v204, v204
	v_log_f32_e32 v205, v205
	v_cvt_pk_bf16_f32 v213, v33, s0
	v_log_f32_e32 v206, v206
	v_log_f32_e32 v207, v207
	ds_write_b16 v110, v213 offset:496
	v_pk_add_f32 v[68:69], v[68:69], 1.0 op_sel_hi:[1,0] neg_lo:[1,0] neg_hi:[1,0]
	v_pk_add_f32 v[72:73], v[72:73], 1.0 op_sel_hi:[1,0] neg_lo:[1,0] neg_hi:[1,0]
	v_pk_add_f32 v[74:75], v[74:75], 1.0 op_sel_hi:[1,0] neg_lo:[1,0] neg_hi:[1,0]
	v_cvt_pk_bf16_f32 v214, v34, s0
	v_pk_add_f32 v[60:61], v[60:61], 1.0 op_sel_hi:[1,0] neg_lo:[1,0] neg_hi:[1,0]
	v_pk_add_f32 v[70:71], v[70:71], 1.0 op_sel_hi:[1,0] neg_lo:[1,0] neg_hi:[1,0]
	ds_write_b16 v110, v214 offset:768
	v_pk_add_f32 v[66:67], v[66:67], 1.0 op_sel_hi:[1,0] neg_lo:[1,0] neg_hi:[1,0]
	v_pk_add_f32 v[64:65], v[64:65], 1.0 op_sel_hi:[1,0] neg_lo:[1,0] neg_hi:[1,0]
	v_max_f32_e32 v192, 0xc2c80000, v192
	v_cvt_pk_bf16_f32 v215, v35, s0
	v_max_f32_e32 v193, 0xc2c80000, v193
	v_max_f32_e32 v194, 0xc2c80000, v194
	ds_write_b16 v110, v215 offset:1040
	v_max_f32_e32 v195, 0xc2c80000, v195
	v_max_f32_e32 v196, 0xc2c80000, v196
	v_max_f32_e32 v197, 0xc2c80000, v197
	v_max_f32_e32 v198, 0xc2c80000, v198
	v_max_f32_e32 v199, 0xc2c80000, v199
	v_max_f32_e32 v200, 0xc2c80000, v200
	v_max_f32_e32 v201, 0xc2c80000, v201
	v_max_f32_e32 v202, 0xc2c80000, v202
	v_max_f32_e32 v203, 0xc2c80000, v203
	v_max_f32_e32 v204, 0xc2c80000, v204
	v_max_f32_e32 v205, 0xc2c80000, v205
	v_max_f32_e32 v206, 0xc2c80000, v206
	v_max_f32_e32 v207, 0xc2c80000, v207
	v_add_f32_e32 v62, 0, v192
	v_add_f32_e32 v123, v62, v193
	v_add_f32_e32 v122, v123, v194
	v_add_f32_e32 v121, v122, v195
	v_add_f32_e32 v120, v121, v196
	v_add_f32_e32 v79, v120, v197
	v_add_f32_e32 v78, v79, v198
	v_add_f32_e32 v124, v78, v199
	v_add_f32_e32 v83, v124, v200
	v_add_f32_e32 v119, v83, v201
	v_add_f32_e32 v118, v119, v202
	v_add_f32_e32 v82, v118, v203
	v_add_f32_e32 v81, v82, v204
	v_add_f32_e32 v80, v81, v205
	v_add_f32_e32 v3, v80, v206
	v_add_f32_e32 v127, v3, v207
	ds_write_b32 v92, v127
	s_waitcnt lgkmcnt(0)
	s_barrier
	ds_read2st64_b32 v[76:77], v93 offset1:2
	ds_read2st64_b32 v[128:129], v93 offset0:4 offset1:6
	v_pk_add_f32 v[0:1], v[0:1], 1.0 op_sel_hi:[1,0] neg_lo:[1,0] neg_hi:[1,0]
	s_waitcnt lgkmcnt(1)
	v_cndmask_b32_e64 v63, 0, v76, s[42:43]
	v_cndmask_b32_e64 v125, 0, v77, s[44:45]
	v_add_f32_e32 v131, v63, v125
	s_waitcnt lgkmcnt(0)
	v_cndmask_b32_e64 v133, 0, v128, s[46:47]
	v_mov_b32_e32 v130, v128
	v_mov_b32_e32 v132, v129
	v_add_f32_e32 v126, v76, v77
	v_pk_add_f32 v[76:77], v[130:131], v[132:133]
	v_pk_mul_f32 v[0:1], v[86:87], v[0:1]
	v_add_f32_e32 v125, v62, v77
	ds_read_u16 v62, v109
	v_exp_f32_e32 v63, v125
	v_add_f32_e32 v3, v3, v77
	s_waitcnt lgkmcnt(0)
	v_lshlrev_b32_e32 v62, 16, v62
	v_mul_f32_e32 v128, v63, v62
	v_min_f32_e64 v62, -v125, s36
	v_exp_f32_e32 v130, v62
	v_pk_add_f32 v[62:63], v[126:127], v[76:77]
	s_nop 0
	v_sub_f32_e32 v76, v62, v125
	v_exp_f32_e32 v126, v76
	v_cvt_pk_bf16_f32 v76, v128, s0
	ds_write_b16 v109, v76
	v_add_f32_e32 v76, v123, v77
	ds_read_u16 v123, v109 offset:272
	v_exp_f32_e32 v125, v76
	v_pk_mul_f32 v[128:129], v[86:87], v[68:69]
	s_waitcnt lgkmcnt(0)
	v_lshlrev_b32_e32 v123, 16, v123
	v_mul_f32_e32 v123, v125, v123
	v_min_f32_e64 v125, -v76, s36
	v_exp_f32_e32 v125, v125
	v_sub_f32_e32 v76, v62, v76
	v_exp_f32_e32 v127, v76
	v_mul_f32_e32 v76, v128, v130
	v_cvt_pk_bf16_f32 v76, v76, s0
	ds_write_b16 v109, v76 offset:17408
	v_mul_f32_e32 v76, v129, v125
	v_cvt_pk_bf16_f32 v76, v76, s0
	ds_write_b16 v109, v76 offset:17680
	v_add_f32_e32 v76, v122, v77
	ds_read_u16 v122, v109 offset:544
	v_cvt_pk_bf16_f32 v123, v123, s0
	ds_write_b16 v109, v123 offset:272
	v_exp_f32_e32 v123, v76
	v_pk_mul_f32 v[68:69], v[128:129], v[126:127]
	s_waitcnt lgkmcnt(1)
	v_lshlrev_b32_e32 v122, 16, v122
	v_pk_mul_f32 v[126:127], v[86:87], v[72:73]
	v_mul_f32_e32 v123, v123, v122
	v_min_f32_e64 v122, -v76, s36
	v_sub_f32_e32 v76, v62, v76
	v_exp_f32_e32 v125, v122
	v_exp_f32_e32 v122, v76
	v_cvt_pk_bf16_f32 v76, v123, s0
	ds_write_b16 v109, v76 offset:544
	v_add_f32_e32 v76, v121, v77
	ds_read_u16 v121, v109 offset:816
	v_exp_f32_e32 v123, v76
	s_waitcnt lgkmcnt(0)
	v_lshlrev_b32_e32 v121, 16, v121
	v_mul_f32_e32 v121, v123, v121
	v_min_f32_e64 v123, -v76, s36
	v_exp_f32_e32 v128, v123
	v_sub_f32_e32 v76, v62, v76
	v_exp_f32_e32 v123, v76
	v_mul_f32_e32 v76, v126, v125
	v_cvt_pk_bf16_f32 v76, v76, s0
	ds_write_b16 v109, v76 offset:17952
	v_mul_f32_e32 v76, v127, v128
	v_cvt_pk_bf16_f32 v76, v76, s0
	ds_write_b16 v109, v76 offset:18224
	v_add_f32_e32 v76, v120, v77
	ds_read_u16 v120, v109 offset:1088
	v_cvt_pk_bf16_f32 v121, v121, s0
	ds_write_b16 v109, v121 offset:816
	v_exp_f32_e32 v121, v76
	v_pk_mul_f32 v[72:73], v[126:127], v[122:123]
	s_waitcnt lgkmcnt(1)
	v_lshlrev_b32_e32 v120, 16, v120
	v_pk_mul_f32 v[122:123], v[86:87], v[74:75]
	v_mul_f32_e32 v121, v121, v120
	v_min_f32_e64 v120, -v76, s36
	v_sub_f32_e32 v76, v62, v76
	v_exp_f32_e32 v125, v120
	v_exp_f32_e32 v120, v76
	v_cvt_pk_bf16_f32 v76, v121, s0
	ds_write_b16 v109, v76 offset:1088
	v_add_f32_e32 v76, v79, v77
	ds_read_u16 v79, v109 offset:1360
	v_exp_f32_e32 v121, v76
	s_waitcnt lgkmcnt(0)
; #define LAS __attribute__((address_space(3)))
; __device__ __forceinline__ unsigned pk2(float lo, float hi) { f32x2 v = {lo, hi}; bf16x2_t b = __builtin_convertvector(v, bf16x2_t); return __builtin_bit_cast(unsigned, b); }
; __device__ __forceinline__ unsigned short f2bf(float f) { return (unsigned short)(pk2(f, 0.f) & 0xffffu); }
; __device__ __forceinline__ float bf2f(unsigned short h) { return __uint_as_float(((unsigned)h) << 16); }
; __device__ __forceinline__ float fexp2(float x) { return __builtin_amdgcn_exp2f(x); }
; #define HG_PREFETCH(C) do { _Pragma("unroll") for (int j = 0; j < 2; ++j) { const int id = tid + j * 512; const bf16_t* rp_ = zC + (size_t)hg_row(bl, dir, (C), id >> 4) * 2560 + h * 128 + (id & 15) * 8; \
;         qp_[j] = *(const u32x4*)rp_; fp_[j] = *(const u32x4*)(rp_ + fcol - h * 128); vp_[j] = *(const u32x4*)(rp_ + 1536); } } while (0)
; __device__ __forceinline__ void hgrn_unit(LAS unsigned char* lds, bf16_t* zC, int bl, int h, int dir, float lb, int tid, bf16_t* ob, int ostr, int ocol) {
;     ...
;             for (int i = 0; i < 16; ++i) {
;                 const float bc = bn + bl_[i];
;                 const float q = bf2f(*(const LAS unsigned short*)(lds + HG_QE + (tq * 16 + i) * 272 + k * 2));
;                 const float qe = q * fexp2(bc);
;                 const float kn = kk_[i] * fexp2(fminf(-bc, 110.f));
;                 ke_[i] = kk_[i] * fexp2(btot - bc);
;                 *(LAS unsigned short*)(lds + HG_QE + (tq * 16 + i) * 272 + k * 2) = f2bf(qe);
;                 *(LAS unsigned short*)(lds + HG_KN + (tq * 16 + i) * 272 + k * 2) = f2bf(kn);
;             }
;             u32x4 w0, w1;
;             w0.x = pk2(ke_[0], ke_[1]); w0.y = pk2(ke_[2], ke_[3]); w0.z = pk2(ke_[4], ke_[5]); w0.w = pk2(ke_[6], ke_[7]);
;             w1.x = pk2(ke_[8], ke_[9]); w1.y = pk2(ke_[10], ke_[11]); w1.z = pk2(ke_[12], ke_[13]); w1.w = pk2(ke_[14], ke_[15]);
;             *(LAS u32x4*)(lds + HG_KET + k * 144 + tq * 32) = w0; *(LAS u32x4*)(lds + HG_KET + k * 144 + tq * 32 + 16) = w1;
;             if (tq == 0) ((LAS float*)(lds + HG_EBT))[k] = fexp2(btot);
;         }
;         __syncthreads();
;         if (c + 1 < 32) HG_PREFETCH(c + 1);
	v_lshlrev_b32_e32 v79, 16, v79
	v_mul_f32_e32 v79, v121, v79
	v_min_f32_e64 v121, -v76, s36
	v_exp_f32_e32 v126, v121
	v_sub_f32_e32 v76, v62, v76
	v_exp_f32_e32 v121, v76
	v_mul_f32_e32 v76, v122, v125
	v_cvt_pk_bf16_f32 v76, v76, s0
	ds_write_b16 v109, v76 offset:18496
	v_mul_f32_e32 v76, v123, v126
	v_cvt_pk_bf16_f32 v76, v76, s0
	ds_write_b16 v109, v76 offset:18768
	v_add_f32_e32 v76, v78, v77
	ds_read_u16 v78, v109 offset:1632
	v_cvt_pk_bf16_f32 v79, v79, s0
	ds_write_b16 v109, v79 offset:1360
	v_exp_f32_e32 v79, v76
	v_pk_mul_f32 v[74:75], v[122:123], v[120:121]
	s_waitcnt lgkmcnt(1)
	v_lshlrev_b32_e32 v78, 16, v78
	v_mul_f32_e32 v79, v79, v78
	v_min_f32_e64 v78, -v76, s36
	v_sub_f32_e32 v76, v62, v76
	v_exp_f32_e32 v122, v78
	v_exp_f32_e32 v78, v76
	v_cvt_pk_bf16_f32 v76, v79, s0
	ds_read_u16 v79, v109 offset:1904
	ds_write_b16 v109, v76 offset:1632
	v_add_f32_e32 v76, v124, v77
	v_exp_f32_e32 v120, v76
	s_waitcnt lgkmcnt(1)
	v_lshlrev_b32_e32 v79, 16, v79
	v_mul_f32_e32 v123, v120, v79
	v_min_f32_e64 v79, -v76, s36
	v_sub_f32_e32 v76, v62, v76
	v_exp_f32_e32 v124, v79
	v_exp_f32_e32 v79, v76
	v_pk_mul_f32 v[120:121], v[86:87], v[60:61]
	s_nop 0
	v_mul_f32_e32 v76, v120, v122
	v_cvt_pk_bf16_f32 v76, v76, s0
	v_pk_mul_f32 v[60:61], v[120:121], v[78:79]
	ds_write_b16 v109, v76 offset:19040
	v_mul_f32_e32 v76, v121, v124
	v_cvt_pk_bf16_f32 v78, v123, s0
	ds_write_b16 v109, v78 offset:1904
	v_cvt_pk_bf16_f32 v76, v76, s0
	ds_read_u16 v78, v109 offset:2176
	ds_write_b16 v109, v76 offset:19312
	v_add_f32_e32 v76, v83, v77
	v_exp_f32_e32 v79, v76
	v_pk_mul_f32 v[120:121], v[86:87], v[70:71]
	s_waitcnt lgkmcnt(1)
	v_lshlrev_b32_e32 v78, 16, v78
	v_mul_f32_e32 v79, v79, v78
	v_min_f32_e64 v78, -v76, s36
	v_sub_f32_e32 v76, v62, v76
	v_exp_f32_e32 v83, v78
	v_exp_f32_e32 v78, v76
	v_cvt_pk_bf16_f32 v76, v79, s0
	ds_read_u16 v79, v109 offset:2448
	ds_write_b16 v109, v76 offset:2176
	v_add_f32_e32 v76, v119, v77
	v_exp_f32_e32 v119, v76
	s_waitcnt lgkmcnt(1)
	v_lshlrev_b32_e32 v79, 16, v79
	v_mul_f32_e32 v119, v119, v79
	v_min_f32_e64 v79, -v76, s36
	v_sub_f32_e32 v76, v62, v76
	v_exp_f32_e32 v122, v79
	v_exp_f32_e32 v79, v76
	v_mul_f32_e32 v76, v120, v83
	v_cvt_pk_bf16_f32 v76, v76, s0
	ds_write_b16 v109, v76 offset:19584
	v_pk_mul_f32 v[70:71], v[120:121], v[78:79]
	v_mul_f32_e32 v76, v121, v122
	v_cvt_pk_bf16_f32 v78, v119, s0
	ds_write_b16 v109, v78 offset:2448
	v_cvt_pk_bf16_f32 v76, v76, s0
	ds_read_u16 v78, v109 offset:2720
	ds_write_b16 v109, v76 offset:19856
	v_add_f32_e32 v76, v118, v77
	v_exp_f32_e32 v79, v76
	s_waitcnt lgkmcnt(1)
	v_lshlrev_b32_e32 v78, 16, v78
	v_mul_f32_e32 v79, v79, v78
	v_min_f32_e64 v78, -v76, s36
	v_sub_f32_e32 v76, v62, v76
	v_exp_f32_e32 v118, v78
	v_exp_f32_e32 v78, v76
	v_cvt_pk_bf16_f32 v76, v79, s0
	ds_read_u16 v79, v109 offset:2992
	ds_write_b16 v109, v76 offset:2720
	v_add_f32_e32 v76, v82, v77
	v_exp_f32_e32 v82, v76
	s_waitcnt lgkmcnt(1)
	v_lshlrev_b32_e32 v79, 16, v79
	v_mul_f32_e32 v119, v82, v79
	v_min_f32_e64 v79, -v76, s36
	v_sub_f32_e32 v76, v62, v76
	v_exp_f32_e32 v120, v79
	v_exp_f32_e32 v79, v76
	v_pk_mul_f32 v[82:83], v[86:87], v[66:67]
	s_nop 0
	v_mul_f32_e32 v76, v82, v118
	v_cvt_pk_bf16_f32 v76, v76, s0
	v_pk_mul_f32 v[66:67], v[82:83], v[78:79]
	ds_write_b16 v109, v76 offset:20128
	v_mul_f32_e32 v76, v83, v120
	v_cvt_pk_bf16_f32 v78, v119, s0
	ds_write_b16 v109, v78 offset:2992
	v_cvt_pk_bf16_f32 v76, v76, s0
	ds_read_u16 v78, v109 offset:3264
	ds_write_b16 v109, v76 offset:20400
	v_add_f32_e32 v76, v81, v77
	v_exp_f32_e32 v79, v76
	s_waitcnt lgkmcnt(1)
	v_lshlrev_b32_e32 v78, 16, v78
	v_mul_f32_e32 v79, v79, v78
	v_min_f32_e64 v78, -v76, s36
	v_sub_f32_e32 v76, v62, v76
	v_exp_f32_e32 v82, v78
	v_exp_f32_e32 v78, v76
	v_cvt_pk_bf16_f32 v76, v79, s0
	ds_read_u16 v79, v109 offset:3536
	ds_write_b16 v109, v76 offset:3264
	v_add_f32_e32 v76, v80, v77
	v_exp_f32_e32 v80, v76
	v_exp_f32_e32 v77, v3
	s_waitcnt lgkmcnt(1)
	v_lshlrev_b32_e32 v79, 16, v79
	v_mul_f32_e32 v83, v80, v79
	v_min_f32_e64 v79, -v76, s36
	v_exp_f32_e32 v118, v79
	v_sub_f32_e32 v76, v62, v76
	v_pk_mul_f32 v[80:81], v[86:87], v[64:65]
	v_exp_f32_e32 v79, v76
	v_mul_f32_e32 v76, v80, v82
	v_cvt_pk_bf16_f32 v76, v76, s0
	ds_write_b16 v109, v76 offset:20672
	v_mul_f32_e32 v76, v81, v118
	v_cvt_pk_bf16_f32 v76, v76, s0
	ds_write_b16 v109, v76 offset:20944
	ds_read_u16 v76, v109 offset:3808
	v_pk_mul_f32 v[64:65], v[80:81], v[78:79]
	v_cvt_pk_bf16_f32 v78, v83, s0
	ds_write_b16 v109, v78 offset:3536
	v_cvt_pk_bf16_f32 v80, v74, v75
	s_waitcnt lgkmcnt(1)
	v_lshlrev_b32_e32 v76, 16, v76
	v_mul_f32_e32 v77, v77, v76
	v_min_f32_e64 v76, -v3, s36
	v_sub_f32_e32 v3, v62, v3
	v_exp_f32_e32 v78, v76
	v_exp_f32_e32 v76, v3
	v_cvt_pk_bf16_f32 v3, v77, s0
	ds_write_b16 v109, v3 offset:3808
	ds_read_u16 v3, v109 offset:4080
	v_exp_f32_e32 v77, v63
	v_cvt_pk_bf16_f32 v81, v60, v61
	s_waitcnt lgkmcnt(0)
	v_lshlrev_b32_e32 v3, 16, v3
	v_mul_f32_e32 v3, v77, v3
	v_min_f32_e64 v77, -v63, s36
	v_exp_f32_e32 v79, v77
	v_sub_f32_e32 v63, v62, v63
	v_exp_f32_e32 v77, v63
	v_mul_f32_e32 v63, v0, v78
	v_cvt_pk_bf16_f32 v63, v63, s0
	ds_write_b16 v109, v63 offset:21216
	v_mul_f32_e32 v63, v1, v79
	v_cvt_pk_bf16_f32 v3, v3, s0
	ds_write_b16 v109, v3 offset:4080
	v_cvt_pk_bf16_f32 v3, v63, s0
	v_cvt_pk_bf16_f32 v78, v68, v69
	v_cvt_pk_bf16_f32 v79, v72, v73
	v_pk_mul_f32 v[0:1], v[0:1], v[76:77]
	ds_write_b16 v109, v3 offset:21488
	v_cvt_pk_bf16_f32 v68, v70, v71
	v_cvt_pk_bf16_f32 v69, v66, v67
	v_cvt_pk_bf16_f32 v70, v64, v65
	v_cvt_pk_bf16_f32 v71, v0, v1
	ds_write_b128 v111, v[78:81] offset:34816
	ds_write_b128 v111, v[68:71] offset:34832
	s_and_saveexec_b64 s[90:91], s[48:49]
	v_exp_f32_e32 v0, v62
	ds_write_b32 v96, v0
	s_or_b64 exec, exec, s[90:91]
	s_cmpk_eq_i32 s63, 0x7c0
	s_waitcnt lgkmcnt(0)
	s_barrier
	s_cbranch_scc1 .LBB0_193
	v_add_u32_e32 v0, s63, v103
	v_cndmask_b32_e32 v0, v104, v0, vcc
	v_add_u32_e32 v0, s62, v0
	v_mad_i64_i32 v[0:1], s[14:15], v0, s8, v[84:85]
	v_lshl_add_u64 v[8:9], v[0:1], 0, s[58:59]
	v_lshl_add_u64 v[16:17], v[8:9], 0, s[88:89]
	global_load_dwordx4 v[8:11], v[0:1], off
	global_load_dwordx4 v[12:15], v[0:1], off offset:3072
	v_add_u32_e32 v0, s63, v101
	v_cndmask_b32_e32 v0, v102, v0, vcc
	v_add_u32_e32 v0, s62, v0
	v_mad_i64_i32 v[0:1], s[14:15], v0, s8, v[84:85]
	v_lshl_add_u64 v[24:25], v[0:1], 0, s[58:59]
	v_lshl_add_u64 v[24:25], v[24:25], 0, s[88:89]
	global_load_dwordx4 v[16:19], v[16:17], off offset:1024
	s_nop 0
	global_load_dwordx4 v[20:23], v[0:1], off
	s_nop 0
	global_load_dwordx4 v[24:27], v[24:25], off offset:1024
	s_nop 0
	global_load_dwordx4 v[28:31], v[0:1], off offset:3072
	s_branch .LBB0_193
